# barrier arrival waits only for the arrival atomic; the L1 invalidate completes in the background (covered by later waits)
# speedup vs baseline: 1.0067x; 1.0067x over previous
; __device__ __forceinline__ unsigned xb_ld(unsigned* p)              { return __hip_atomic_load(p, __ATOMIC_RELAXED, __HIP_MEMORY_SCOPE_AGENT); }
; __device__ __forceinline__ unsigned xb_add(unsigned* p, unsigned v) { return __hip_atomic_fetch_add(p, v, __ATOMIC_RELAXED, __HIP_MEMORY_SCOPE_AGENT); }
; #define XB_SPIN(cond, bar) do { unsigned _sp = 0; while (cond) { __builtin_amdgcn_s_sleep(1); \
;     if ((++_sp & 255u) == 0u) { if (xb_ld(&(bar)[XB_TMO])) break; if (_sp > XB_SPIN_CAP) { atomicAdd(&(bar)[XB_TMO], 1u); break; } } } } while (0)
; __device__ __forceinline__ void xcd_barrier(const XcdBarrier& b, int wv) {
;     ...
;         const unsigned old = xb_add(&bar[XB_XSUB(bx)], 1u);
;         const unsigned gen = old / nloc;
;         if (old + 1u == (gen + 1u) * nloc) {
;             __builtin_amdgcn_fence(__ATOMIC_RELEASE, "agent");
;             asm volatile("s_waitcnt vmcnt(0)" ::: "memory");
;             const unsigned og = xb_add(&bar[XB_TOP], 1u);
;             const unsigned tg = og / nx;
;             if (og + 1u == (tg + 1u) * nx) xb_add(&bar[XB_TOPGEN], 1u);
;             else XB_SPIN(xb_ld(&bar[XB_TOPGEN]) == tg, bar);
;             __builtin_amdgcn_fence(__ATOMIC_ACQUIRE, "agent");
;             xb_add(&bar[XB_XGEN(bx)], 1u);
;             asm volatile("s_waitcnt vmcnt(0)" ::: "memory");
;         } else {
;             XB_SPIN(xb_ld(&bar[XB_XGEN(bx)]) == gen, bar);
.LBB0_142:
	s_or_b64 exec, exec, s[6:7]
	v_cvt_f32_u32_e32 v4, v2
	s_waitcnt vmcnt(1)
	v_readfirstlane_b32 s4, v3
	v_sub_u32_e32 v3, 0, v2
	v_rcp_iflag_f32_e32 v4, v4
	v_add_u32_e32 v5, s4, v1
	v_mul_f32_e32 v4, 0x4f7ffffe, v4
	v_cvt_u32_f32_e32 v4, v4
	v_mul_lo_u32 v1, v3, v4
	v_mul_hi_u32 v1, v4, v1
	v_add_u32_e32 v1, v4, v1
	v_mul_hi_u32 v1, v5, v1
	v_mul_lo_u32 v3, v1, v2
	v_sub_u32_e32 v3, v5, v3
	v_add_u32_e32 v4, 1, v1
	v_cmp_ge_u32_e32 vcc, v3, v2
	s_nop 1
	v_cndmask_b32_e32 v1, v1, v4, vcc
	v_sub_u32_e32 v4, v3, v2
	v_cndmask_b32_e32 v3, v3, v4, vcc
	v_add_u32_e32 v4, 1, v1
	v_cmp_ge_u32_e32 vcc, v3, v2
	v_add_u32_e32 v3, 1, v5
	s_nop 0
	v_cndmask_b32_e32 v1, v1, v4, vcc
	v_mul_lo_u32 v4, v2, v1
	v_add_u32_e32 v2, v4, v2
	v_cmp_ne_u32_e32 vcc, v3, v2
	s_and_saveexec_b64 s[4:5], vcc
	s_xor_b64 s[4:5], exec, s[4:5]
	s_cbranch_execz .LBB0_156
	s_movk_i32 s6, 0xd00
	v_mad_u32_u24 v2, v1, v0, v0
	s_nop 0
	v_readfirstlane_b32 s98, v2
	s_mov_b32 s7, 0
	s_lshl_b64 s[6:7], s[6:7], 2
	s_add_u32 s10, s82, s6
	s_addc_u32 s11, s83, s7
	s_waitcnt lgkmcnt(0)
	v_mov_b32_e32 v0, 0
	global_load_dword v2, v0, s[10:11] sc1
	s_waitcnt vmcnt(0)
	v_cmp_gt_u32_e32 vcc, s98, v2
	s_and_saveexec_b64 s[6:7], vcc
	s_cbranch_execz .LBB0_155
	s_add_u32 s8, s30, 0x3e9200
	s_addc_u32 s9, s31, 0
	s_mov_b32 s36, 1
	s_mov_b64 s[12:13], 0
	s_branch .LBB0_146

; __device__ __forceinline__ unsigned xb_ld(unsigned* p)              { return __hip_atomic_load(p, __ATOMIC_RELAXED, __HIP_MEMORY_SCOPE_AGENT); }
; __device__ __forceinline__ unsigned xb_add(unsigned* p, unsigned v) { return __hip_atomic_fetch_add(p, v, __ATOMIC_RELAXED, __HIP_MEMORY_SCOPE_AGENT); }
; #define XB_SPIN(cond, bar) do { unsigned _sp = 0; while (cond) { __builtin_amdgcn_s_sleep(1); \
;     if ((++_sp & 255u) == 0u) { if (xb_ld(&(bar)[XB_TMO])) break; if (_sp > XB_SPIN_CAP) { atomicAdd(&(bar)[XB_TMO], 1u); break; } } } } while (0)
; __device__ __forceinline__ void xcd_barrier(const XcdBarrier& b, int wv) {
;     ...
;         const unsigned old = xb_add(&bar[XB_XSUB(bx)], 1u);
;         const unsigned gen = old / nloc;
;         if (old + 1u == (gen + 1u) * nloc) {
;             __builtin_amdgcn_fence(__ATOMIC_RELEASE, "agent");
;             asm volatile("s_waitcnt vmcnt(0)" ::: "memory");
;             const unsigned og = xb_add(&bar[XB_TOP], 1u);
;             const unsigned tg = og / nx;
;             if (og + 1u == (tg + 1u) * nx) xb_add(&bar[XB_TOPGEN], 1u);
;             else XB_SPIN(xb_ld(&bar[XB_TOPGEN]) == tg, bar);
;             __builtin_amdgcn_fence(__ATOMIC_ACQUIRE, "agent");
;             xb_add(&bar[XB_XGEN(bx)], 1u);
;             asm volatile("s_waitcnt vmcnt(0)" ::: "memory");
;         } else {
;             XB_SPIN(xb_ld(&bar[XB_XGEN(bx)]) == gen, bar);
.LBB0_243:
	s_or_b64 exec, exec, s[14:15]
	v_cvt_f32_u32_e32 v5, v3
	s_waitcnt vmcnt(1)
	v_readfirstlane_b32 s10, v4
	v_sub_u32_e32 v4, 0, v3
	v_rcp_iflag_f32_e32 v5, v5
	v_add_u32_e32 v6, s10, v1
	v_mul_f32_e32 v5, 0x4f7ffffe, v5
	v_cvt_u32_f32_e32 v5, v5
	v_mul_lo_u32 v1, v4, v5
	v_mul_hi_u32 v1, v5, v1
	v_add_u32_e32 v1, v5, v1
	v_mul_hi_u32 v1, v6, v1
	v_mul_lo_u32 v4, v1, v3
	v_sub_u32_e32 v4, v6, v4
	v_add_u32_e32 v5, 1, v1
	v_cmp_ge_u32_e32 vcc, v4, v3
	s_nop 1
	v_cndmask_b32_e32 v1, v1, v5, vcc
	v_sub_u32_e32 v5, v4, v3
	v_cndmask_b32_e32 v4, v4, v5, vcc
	v_add_u32_e32 v5, 1, v1
	v_cmp_ge_u32_e32 vcc, v4, v3
	v_add_u32_e32 v4, 1, v6
	s_nop 0
	v_cndmask_b32_e32 v1, v1, v5, vcc
	v_mul_lo_u32 v5, v3, v1
	v_add_u32_e32 v3, v5, v3
	v_cmp_ne_u32_e32 vcc, v4, v3
	s_and_saveexec_b64 s[10:11], vcc
	s_xor_b64 s[10:11], exec, s[10:11]
	s_cbranch_execz .LBB0_257
	s_movk_i32 s36, 0xd00
	v_mad_u32_u24 v2, v1, v2, v2
	s_nop 0
	v_readfirstlane_b32 s98, v2
	s_lshl_b64 s[14:15], s[36:37], 2
	s_add_u32 s16, s82, s14
	s_addc_u32 s17, s83, s15
	s_waitcnt lgkmcnt(0)
	global_load_dword v2, v0, s[16:17] sc1
	s_waitcnt vmcnt(0)
	v_cmp_gt_u32_e32 vcc, s98, v2
	s_and_saveexec_b64 s[14:15], vcc
	s_cbranch_execz .LBB0_256
	s_mov_b32 s36, 1
	s_mov_b64 s[20:21], 0
	s_branch .LBB0_247

; __device__ __forceinline__ unsigned xb_ld(unsigned* p)              { return __hip_atomic_load(p, __ATOMIC_RELAXED, __HIP_MEMORY_SCOPE_AGENT); }
; __device__ __forceinline__ unsigned xb_add(unsigned* p, unsigned v) { return __hip_atomic_fetch_add(p, v, __ATOMIC_RELAXED, __HIP_MEMORY_SCOPE_AGENT); }
; #define XB_SPIN(cond, bar) do { unsigned _sp = 0; while (cond) { __builtin_amdgcn_s_sleep(1); \
;     if ((++_sp & 255u) == 0u) { if (xb_ld(&(bar)[XB_TMO])) break; if (_sp > XB_SPIN_CAP) { atomicAdd(&(bar)[XB_TMO], 1u); break; } } } } while (0)
; __device__ __forceinline__ void xcd_barrier(const XcdBarrier& b, int wv) {
;     ...
;         const unsigned old = xb_add(&bar[XB_XSUB(bx)], 1u);
;         const unsigned gen = old / nloc;
;         if (old + 1u == (gen + 1u) * nloc) {
;             __builtin_amdgcn_fence(__ATOMIC_RELEASE, "agent");
;             asm volatile("s_waitcnt vmcnt(0)" ::: "memory");
;             const unsigned og = xb_add(&bar[XB_TOP], 1u);
;             const unsigned tg = og / nx;
;             if (og + 1u == (tg + 1u) * nx) xb_add(&bar[XB_TOPGEN], 1u);
;             else XB_SPIN(xb_ld(&bar[XB_TOPGEN]) == tg, bar);
;             __builtin_amdgcn_fence(__ATOMIC_ACQUIRE, "agent");
;             xb_add(&bar[XB_XGEN(bx)], 1u);
;             asm volatile("s_waitcnt vmcnt(0)" ::: "memory");
;         } else {
;             XB_SPIN(xb_ld(&bar[XB_XGEN(bx)]) == gen, bar);
.LBB0_351:
	s_or_b64 exec, exec, s[10:11]
	v_cvt_f32_u32_e32 v5, v3
	s_waitcnt vmcnt(1)
	v_readfirstlane_b32 s6, v4
	v_sub_u32_e32 v4, 0, v3
	v_rcp_iflag_f32_e32 v5, v5
	v_add_u32_e32 v6, s6, v1
	v_mul_f32_e32 v5, 0x4f7ffffe, v5
	v_cvt_u32_f32_e32 v5, v5
	v_mul_lo_u32 v1, v4, v5
	v_mul_hi_u32 v1, v5, v1
	v_add_u32_e32 v1, v5, v1
	v_mul_hi_u32 v1, v6, v1
	v_mul_lo_u32 v4, v1, v3
	v_sub_u32_e32 v4, v6, v4
	v_add_u32_e32 v5, 1, v1
	v_cmp_ge_u32_e32 vcc, v4, v3
	s_nop 1
	v_cndmask_b32_e32 v1, v1, v5, vcc
	v_sub_u32_e32 v5, v4, v3
	v_cndmask_b32_e32 v4, v4, v5, vcc
	v_add_u32_e32 v5, 1, v1
	v_cmp_ge_u32_e32 vcc, v4, v3
	v_add_u32_e32 v4, 1, v6
	s_nop 0
	v_cndmask_b32_e32 v1, v1, v5, vcc
	v_mul_lo_u32 v5, v3, v1
	v_add_u32_e32 v3, v5, v3
	v_cmp_ne_u32_e32 vcc, v4, v3
	s_and_saveexec_b64 s[6:7], vcc
	s_xor_b64 s[6:7], exec, s[6:7]
	s_cbranch_execz .LBB0_365
	s_movk_i32 s36, 0xd00
	v_mad_u32_u24 v2, v1, v2, v2
	s_nop 0
	v_readfirstlane_b32 s98, v2
	s_lshl_b64 s[10:11], s[36:37], 2
	s_add_u32 s14, s82, s10
	s_addc_u32 s15, s83, s11
	s_waitcnt lgkmcnt(0)
	global_load_dword v2, v0, s[14:15] sc1
	s_waitcnt vmcnt(0)
	v_cmp_gt_u32_e32 vcc, s98, v2
	s_and_saveexec_b64 s[10:11], vcc
	s_cbranch_execz .LBB0_364
	s_mov_b32 s36, 1
	s_mov_b64 s[16:17], 0
	s_branch .LBB0_355

; __device__ __forceinline__ unsigned xb_ld(unsigned* p)              { return __hip_atomic_load(p, __ATOMIC_RELAXED, __HIP_MEMORY_SCOPE_AGENT); }
; __device__ __forceinline__ unsigned xb_add(unsigned* p, unsigned v) { return __hip_atomic_fetch_add(p, v, __ATOMIC_RELAXED, __HIP_MEMORY_SCOPE_AGENT); }
; #define XB_SPIN(cond, bar) do { unsigned _sp = 0; while (cond) { __builtin_amdgcn_s_sleep(1); \
;     if ((++_sp & 255u) == 0u) { if (xb_ld(&(bar)[XB_TMO])) break; if (_sp > XB_SPIN_CAP) { atomicAdd(&(bar)[XB_TMO], 1u); break; } } } } while (0)
; __device__ __forceinline__ void xcd_barrier(const XcdBarrier& b, int wv) {
;     ...
;         const unsigned old = xb_add(&bar[XB_XSUB(bx)], 1u);
;         const unsigned gen = old / nloc;
;         if (old + 1u == (gen + 1u) * nloc) {
;             __builtin_amdgcn_fence(__ATOMIC_RELEASE, "agent");
;             asm volatile("s_waitcnt vmcnt(0)" ::: "memory");
;             const unsigned og = xb_add(&bar[XB_TOP], 1u);
;             const unsigned tg = og / nx;
;             if (og + 1u == (tg + 1u) * nx) xb_add(&bar[XB_TOPGEN], 1u);
;             else XB_SPIN(xb_ld(&bar[XB_TOPGEN]) == tg, bar);
;             __builtin_amdgcn_fence(__ATOMIC_ACQUIRE, "agent");
;             xb_add(&bar[XB_XGEN(bx)], 1u);
;             asm volatile("s_waitcnt vmcnt(0)" ::: "memory");
;         } else {
;             XB_SPIN(xb_ld(&bar[XB_XGEN(bx)]) == gen, bar);
.LBB0_525:
	s_or_b64 exec, exec, s[6:7]
	v_cvt_f32_u32_e32 v5, v3
	s_waitcnt vmcnt(1)
	v_readfirstlane_b32 s4, v4
	v_sub_u32_e32 v4, 0, v3
	v_rcp_iflag_f32_e32 v5, v5
	v_add_u32_e32 v6, s4, v1
	v_mul_f32_e32 v5, 0x4f7ffffe, v5
	v_cvt_u32_f32_e32 v5, v5
	v_mul_lo_u32 v1, v4, v5
	v_mul_hi_u32 v1, v5, v1
	v_add_u32_e32 v1, v5, v1
	v_mul_hi_u32 v1, v6, v1
	v_mul_lo_u32 v4, v1, v3
	v_sub_u32_e32 v4, v6, v4
	v_add_u32_e32 v5, 1, v1
	v_cmp_ge_u32_e32 vcc, v4, v3
	s_nop 1
	v_cndmask_b32_e32 v1, v1, v5, vcc
	v_sub_u32_e32 v5, v4, v3
	v_cndmask_b32_e32 v4, v4, v5, vcc
	v_add_u32_e32 v5, 1, v1
	v_cmp_ge_u32_e32 vcc, v4, v3
	v_add_u32_e32 v4, 1, v6
	s_nop 0
	v_cndmask_b32_e32 v1, v1, v5, vcc
	v_mul_lo_u32 v5, v3, v1
	v_add_u32_e32 v3, v5, v3
	v_cmp_ne_u32_e32 vcc, v4, v3
	s_and_saveexec_b64 s[4:5], vcc
	s_xor_b64 s[4:5], exec, s[4:5]
	s_cbranch_execz .LBB0_539
	s_movk_i32 s36, 0xd00
	v_mad_u32_u24 v2, v1, v2, v2
	s_nop 0
	v_readfirstlane_b32 s98, v2
	s_lshl_b64 s[6:7], s[36:37], 2
	s_add_u32 s8, s82, s6
	s_addc_u32 s9, s83, s7
	s_waitcnt lgkmcnt(0)
	global_load_dword v2, v0, s[8:9] sc1
	s_waitcnt vmcnt(0)
	v_cmp_gt_u32_e32 vcc, s98, v2
	s_and_saveexec_b64 s[6:7], vcc
	s_cbranch_execz .LBB0_538
	s_mov_b32 s36, 1
	s_mov_b64 s[10:11], 0
	s_branch .LBB0_529

; __device__ __forceinline__ unsigned xb_ld(unsigned* p)              { return __hip_atomic_load(p, __ATOMIC_RELAXED, __HIP_MEMORY_SCOPE_AGENT); }
; __device__ __forceinline__ unsigned xb_add(unsigned* p, unsigned v) { return __hip_atomic_fetch_add(p, v, __ATOMIC_RELAXED, __HIP_MEMORY_SCOPE_AGENT); }
; #define XB_SPIN(cond, bar) do { unsigned _sp = 0; while (cond) { __builtin_amdgcn_s_sleep(1); \
;     if ((++_sp & 255u) == 0u) { if (xb_ld(&(bar)[XB_TMO])) break; if (_sp > XB_SPIN_CAP) { atomicAdd(&(bar)[XB_TMO], 1u); break; } } } } while (0)
; __device__ __forceinline__ void xcd_barrier(const XcdBarrier& b, int wv) {
;     ...
;         const unsigned old = xb_add(&bar[XB_XSUB(bx)], 1u);
;         const unsigned gen = old / nloc;
;         if (old + 1u == (gen + 1u) * nloc) {
;             __builtin_amdgcn_fence(__ATOMIC_RELEASE, "agent");
;             asm volatile("s_waitcnt vmcnt(0)" ::: "memory");
;             const unsigned og = xb_add(&bar[XB_TOP], 1u);
;             const unsigned tg = og / nx;
;             if (og + 1u == (tg + 1u) * nx) xb_add(&bar[XB_TOPGEN], 1u);
;             else XB_SPIN(xb_ld(&bar[XB_TOPGEN]) == tg, bar);
;             __builtin_amdgcn_fence(__ATOMIC_ACQUIRE, "agent");
;             xb_add(&bar[XB_XGEN(bx)], 1u);
;             asm volatile("s_waitcnt vmcnt(0)" ::: "memory");
;         } else {
;             XB_SPIN(xb_ld(&bar[XB_XGEN(bx)]) == gen, bar);
.LBB0_764:
	s_or_b64 exec, exec, s[6:7]
	v_cvt_f32_u32_e32 v5, v3
	s_waitcnt vmcnt(1)
	v_readfirstlane_b32 s4, v4
	v_sub_u32_e32 v4, 0, v3
	v_rcp_iflag_f32_e32 v5, v5
	v_add_u32_e32 v6, s4, v1
	v_mul_f32_e32 v5, 0x4f7ffffe, v5
	v_cvt_u32_f32_e32 v5, v5
	v_mul_lo_u32 v1, v4, v5
	v_mul_hi_u32 v1, v5, v1
	v_add_u32_e32 v1, v5, v1
	v_mul_hi_u32 v1, v6, v1
	v_mul_lo_u32 v4, v1, v3
	v_sub_u32_e32 v4, v6, v4
	v_add_u32_e32 v5, 1, v1
	v_cmp_ge_u32_e32 vcc, v4, v3
	s_nop 1
	v_cndmask_b32_e32 v1, v1, v5, vcc
	v_sub_u32_e32 v5, v4, v3
	v_cndmask_b32_e32 v4, v4, v5, vcc
	v_add_u32_e32 v5, 1, v1
	v_cmp_ge_u32_e32 vcc, v4, v3
	v_add_u32_e32 v4, 1, v6
	s_nop 0
	v_cndmask_b32_e32 v1, v1, v5, vcc
	v_mul_lo_u32 v5, v3, v1
	v_add_u32_e32 v3, v5, v3
	v_cmp_ne_u32_e32 vcc, v4, v3
	s_and_saveexec_b64 s[4:5], vcc
	s_xor_b64 s[4:5], exec, s[4:5]
	s_cbranch_execz .LBB0_778
	s_movk_i32 s36, 0xd00
	v_mad_u32_u24 v2, v1, v2, v2
	s_nop 0
	v_readfirstlane_b32 s98, v2
	s_lshl_b64 s[6:7], s[36:37], 2
	s_add_u32 s8, s82, s6
	s_addc_u32 s9, s83, s7
	s_waitcnt lgkmcnt(0)
	global_load_dword v2, v0, s[8:9] sc1
	s_waitcnt vmcnt(0)
	v_cmp_gt_u32_e32 vcc, s98, v2
	s_and_saveexec_b64 s[6:7], vcc
	s_cbranch_execz .LBB0_777
	s_mov_b32 s36, 1
	s_mov_b64 s[12:13], 0
	s_branch .LBB0_768

; __device__ __forceinline__ unsigned xb_ld(unsigned* p)              { return __hip_atomic_load(p, __ATOMIC_RELAXED, __HIP_MEMORY_SCOPE_AGENT); }
; __device__ __forceinline__ unsigned xb_add(unsigned* p, unsigned v) { return __hip_atomic_fetch_add(p, v, __ATOMIC_RELAXED, __HIP_MEMORY_SCOPE_AGENT); }
; #define XB_SPIN(cond, bar) do { unsigned _sp = 0; while (cond) { __builtin_amdgcn_s_sleep(1); \
;     if ((++_sp & 255u) == 0u) { if (xb_ld(&(bar)[XB_TMO])) break; if (_sp > XB_SPIN_CAP) { atomicAdd(&(bar)[XB_TMO], 1u); break; } } } } while (0)
; __device__ __forceinline__ void xcd_barrier(const XcdBarrier& b, int wv) {
;     ...
;         const unsigned old = xb_add(&bar[XB_XSUB(bx)], 1u);
;         const unsigned gen = old / nloc;
;         if (old + 1u == (gen + 1u) * nloc) {
;             __builtin_amdgcn_fence(__ATOMIC_RELEASE, "agent");
;             asm volatile("s_waitcnt vmcnt(0)" ::: "memory");
;             const unsigned og = xb_add(&bar[XB_TOP], 1u);
;             const unsigned tg = og / nx;
;             if (og + 1u == (tg + 1u) * nx) xb_add(&bar[XB_TOPGEN], 1u);
;             else XB_SPIN(xb_ld(&bar[XB_TOPGEN]) == tg, bar);
;             __builtin_amdgcn_fence(__ATOMIC_ACQUIRE, "agent");
;             xb_add(&bar[XB_XGEN(bx)], 1u);
;             asm volatile("s_waitcnt vmcnt(0)" ::: "memory");
;         } else {
;             XB_SPIN(xb_ld(&bar[XB_XGEN(bx)]) == gen, bar);
.LBB0_818:
	s_or_b64 exec, exec, s[10:11]
	v_cvt_f32_u32_e32 v8, v6
	s_waitcnt vmcnt(1)
	v_readfirstlane_b32 s8, v7
	v_sub_u32_e32 v7, 0, v6
	v_rcp_iflag_f32_e32 v8, v8
	v_add_u32_e32 v9, s8, v5
	v_mul_f32_e32 v8, 0x4f7ffffe, v8
	v_cvt_u32_f32_e32 v8, v8
	v_mul_lo_u32 v5, v7, v8
	v_mul_hi_u32 v5, v8, v5
	v_add_u32_e32 v5, v8, v5
	v_mul_hi_u32 v5, v9, v5
	v_mul_lo_u32 v7, v5, v6
	v_sub_u32_e32 v7, v9, v7
	v_add_u32_e32 v8, 1, v5
	v_cmp_ge_u32_e32 vcc, v7, v6
	s_nop 1
	v_cndmask_b32_e32 v5, v5, v8, vcc
	v_sub_u32_e32 v8, v7, v6
	v_cndmask_b32_e32 v7, v7, v8, vcc
	v_add_u32_e32 v8, 1, v5
	v_cmp_ge_u32_e32 vcc, v7, v6
	v_add_u32_e32 v7, 1, v9
	s_nop 0
	v_cndmask_b32_e32 v5, v5, v8, vcc
	v_mul_lo_u32 v8, v6, v5
	v_add_u32_e32 v6, v8, v6
	v_cmp_ne_u32_e32 vcc, v7, v6
	s_and_saveexec_b64 s[8:9], vcc
	s_xor_b64 s[8:9], exec, s[8:9]
	s_cbranch_execz .LBB0_832
	s_movk_i32 s10, 0xd00
	v_mad_u32_u24 v6, v5, v4, v4
	s_nop 0
	v_readfirstlane_b32 s98, v6
	s_mov_b32 s11, 0
	s_lshl_b64 s[10:11], s[10:11], 2
	s_add_u32 s12, s82, s10
	s_addc_u32 s13, s83, s11
	s_waitcnt lgkmcnt(0)
	v_mov_b32_e32 v4, 0
	global_load_dword v6, v4, s[12:13] sc1
	s_waitcnt vmcnt(0)
	v_cmp_gt_u32_e32 vcc, s98, v6
	s_and_saveexec_b64 s[10:11], vcc
	s_cbranch_execz .LBB0_831
	s_mov_b32 s25, 1
	s_mov_b64 s[14:15], 0
	s_branch .LBB0_822
